# diff attention fast loop: latch and header fused into the tile body (back-edge rotation) on top of staggered in-body DMA
# speedup vs baseline: 1.0049x; 1.0049x over previous
; template <int DK, int DV, int NM, bool CAUSAL> ...
;     ...
;   for (int kt = 0; kt < nkt; ++kt) {
;     if (kt + 2 < nkt) asm volatile("s_waitcnt vmcnt(%0)" ::"n"(2 * NLD) : "memory");
;     else if (kt + 1 < nkt) asm volatile("s_waitcnt vmcnt(%0)" ::"n"(NLD) : "memory");
;     else asm volatile("s_waitcnt vmcnt(0)" ::: "memory");
;     asm volatile("s_waitcnt lgkmcnt(0)" ::: "memory");
;     __builtin_amdgcn_s_barrier();
;     if (kt + 3 < nkt) issue(kt + 3);
;     const bool skip = CAUSAL && (kt * 64 > q0w + 31);
;     if (!skip) {
;       const char* base = smem + (kt & 3) * STAGE;
;       f32x16 s[2];
; #pragma unroll
;       for (int sb = 0; sb < 2; ++sb) {
; #pragma unroll
;         for (int i = 0; i < 16; ++i) s[sb][i] = 0.f;
;         const char* pk = base + (sb * 32 + l31) * 256;
; #pragma unroll
;         for (int kc = 0; kc < NKC16; ++kc) {
;           const bf16x8 a = *(const bf16x8*)(pk + (((mymap * (DK / 8) + kc * 2 + h) ^ (l31 & 15)) * 16));
;           s[sb] = MFMA(a, qf[kc], s[sb]);
;         }
;         __builtin_amdgcn_sched_barrier(0);
;       }
;       const bool need_mask = CAUSAL && (kt * 64 + 63 > q0w);
;       const char* pv = base + KBYTES + l31 * 128;
;       const int vsw = (l31 >> 1) & 7;
;       bf16x8 pf[4];
;       auto expo = [&](int sb) {
; #pragma unroll
;         for (int i = 0; i < 16; ++i) {
;           float pz = __builtin_amdgcn_exp2f(s[sb][i]);
;           if (need_mask) {
;             const int key = kt * 64 + sb * 32 + crow(i, h);
;             if (key > q0w + l31) pz = 0.f;
;           }
;           s[sb][i] = pz;
;         }
; #pragma unroll
;         for (int k2 = 0; k2 < 2; ++k2) {
;           u4 pu;
;           pu.x = pack2(s[sb][k2 * 8 + 0], s[sb][k2 * 8 + 1]);
;           pu.y = pack2(s[sb][k2 * 8 + 2], s[sb][k2 * 8 + 3]);
;           pu.z = pack2(s[sb][k2 * 8 + 4], s[sb][k2 * 8 + 5]);
;           pu.w = pack2(s[sb][k2 * 8 + 6], s[sb][k2 * 8 + 7]);
;           pf[sb * 2 + k2] = __builtin_bit_cast(bf16x8, pu);
;         }
;       };
;       auto pvmm = [&](int ks) {
;         lacc = MFMA(ones, pf[ks], lacc);
; #pragma unroll
;         for (int d = 0; d < NDVB; ++d) {
;           const u4 au = *(const u4*)(pv + d * 32 * 128 + (((ks * 2 + h) ^ vsw) * 16));
;           o[d] = MFMA(__builtin_bit_cast(bf16x8, au), pf[ks], o[d]);
;         }
;       };
;       expo(0);
;       pvmm(0); pvmm(1);
;       expo(1);
.LBB0_95:
	s_waitcnt lgkmcnt(0)
	s_add_i32 s4, s65, 3
	s_cmp_ge_u32 s4, s61
	s_barrier
	s_cbranch_scc1 .LBB0_97
	s_add_i32 s4, s63, 63
	s_cmp_le_u32 s4, s100
	s_cbranch_scc0 .Lmy_d96
	s_cmp_eq_u32 s101, 1
	s_cbranch_scc1 .Lmy_dlate
.Lmy_dearly:
	s_and_b32 s4, s64, 0x18000
	v_or_b32_e32 v0, s4, v170
	v_add_u32_e32 v6, v0, v174
	v_add_u32_e32 v7, v0, v175
	v_add_u32_e32 v8, v0, v173
	v_add_u32_e32 v9, v0, v172
	ds_read_b128 v[212:215], v6
	ds_read_b128 v[216:219], v7
	ds_read_b128 v[220:223], v8
	ds_read_b128 v[224:227], v9
	ds_read_b128 v[228:231], v6 offset:8192
	ds_read_b128 v[232:235], v7 offset:8192
	ds_read_b128 v[236:239], v8 offset:8192
	ds_read_b128 v[240:243], v9 offset:8192
	v_or_b32_e32 v0, s4, v168
	v_add_u32_e32 v10, v0, v167
	v_add_u32_e32 v11, v0, v166
	v_add_u32_e32 v12, v0, v164
	v_add_u32_e32 v13, v0, v163
	v_add_u32_e32 v0, s63, v171
	v_add_u32_e32 v6, 0xc0, v0
	v_add_u32_e32 v8, 0xc4, v0
	v_ashrrev_i32_e32 v7, 31, v6
	v_ashrrev_i32_e32 v9, 31, v8
	v_lshlrev_b64 v[6:7], 11, v[6:7]
	v_lshlrev_b64 v[8:9], 11, v[8:9]
	s_add_i32 s4, s64, 0x18000
	s_and_b32 s4, s4, 0x18000
	v_lshl_add_u64 v[6:7], v[148:149], 0, v[6:7]
	v_lshl_add_u64 v[8:9], v[146:147], 0, v[8:9]
	s_add_i32 s5, s4, s35
	s_add_i32 s4, s4, s60
	s_waitcnt lgkmcnt(7)
	v_mfma_f32_32x32x16_bf16 v[112:127], v[212:215], v[140:143], 0
	s_mov_b32 m0, s5
	s_waitcnt lgkmcnt(6)
	v_mfma_f32_32x32x16_bf16 v[112:127], v[216:219], v[136:139], v[112:127]
	global_load_lds_dwordx4 v[6:7], off
	s_waitcnt lgkmcnt(5)
	v_mfma_f32_32x32x16_bf16 v[112:127], v[220:223], v[132:135], v[112:127]
	s_mov_b32 m0, s4
	s_waitcnt lgkmcnt(4)
	v_mfma_f32_32x32x16_bf16 v[112:127], v[224:227], v[128:131], v[112:127]
	global_load_lds_dwordx4 v[8:9], off
	ds_read_b128 v[212:215], v10 offset:16384
	ds_read_b128 v[216:219], v10 offset:20480
	s_waitcnt lgkmcnt(5)
	v_mfma_f32_32x32x16_bf16 v[96:111], v[228:231], v[140:143], 0
	s_add_i32 m0, s5, 0x4000
	ds_read_b128 v[220:223], v10 offset:24576
	ds_read_b128 v[224:227], v10 offset:28672
	s_waitcnt lgkmcnt(6)
	v_mfma_f32_32x32x16_bf16 v[96:111], v[232:235], v[136:139], v[96:111]
	global_load_lds_dwordx4 v[152:153], off
	s_waitcnt lgkmcnt(5)
	v_mfma_f32_32x32x16_bf16 v[96:111], v[236:239], v[132:135], v[96:111]
	s_add_i32 m0, s4, 0x4000
	s_waitcnt lgkmcnt(4)
	v_mfma_f32_32x32x16_bf16 v[96:111], v[240:243], v[128:131], v[96:111]
	global_load_lds_dwordx4 v[154:155], off
	ds_read_b128 v[228:231], v11 offset:16384
	ds_read_b128 v[232:235], v11 offset:20480
	ds_read_b128 v[236:239], v11 offset:24576
	ds_read_b128 v[240:243], v11 offset:28672
	v_exp_f32_e32 v112, v112
	v_exp_f32_e32 v113, v113
	v_exp_f32_e32 v114, v114
	v_exp_f32_e32 v115, v115
	v_exp_f32_e32 v116, v116
	v_exp_f32_e32 v117, v117
	v_exp_f32_e32 v118, v118
	v_exp_f32_e32 v119, v119
	v_add_f32_e32 v248, v248, v112
	v_add_f32_e32 v249, v249, v113
	v_add_f32_e32 v248, v248, v114
	v_add_f32_e32 v249, v249, v115
	v_add_f32_e32 v248, v248, v116
	v_add_f32_e32 v249, v249, v117
	v_add_f32_e32 v248, v248, v118
	v_add_f32_e32 v249, v249, v119
	v_cvt_pk_bf16_f32 v186, v112, v113
	v_cvt_pk_bf16_f32 v187, v114, v115
	v_cvt_pk_bf16_f32 v188, v116, v117
	v_cvt_pk_bf16_f32 v189, v118, v119
	s_nop 0
	s_waitcnt lgkmcnt(7)
	v_mfma_f32_32x32x16_bf16 v[64:79], v[212:215], v[186:189], v[64:79]
	ds_read_b128 v[212:215], v12 offset:16384
	v_exp_f32_e32 v120, v120
	v_exp_f32_e32 v121, v121
	v_exp_f32_e32 v122, v122
	v_exp_f32_e32 v123, v123
	v_exp_f32_e32 v124, v124
	s_waitcnt lgkmcnt(7)
	v_mfma_f32_32x32x16_bf16 v[48:63], v[216:219], v[186:189], v[48:63]
	ds_read_b128 v[216:219], v12 offset:20480
	v_exp_f32_e32 v125, v125
	v_exp_f32_e32 v126, v126
	v_exp_f32_e32 v127, v127
	v_add_f32_e32 v248, v248, v120
	v_add_f32_e32 v249, v249, v121
	s_waitcnt lgkmcnt(7)
	v_mfma_f32_32x32x16_bf16 v[32:47], v[220:223], v[186:189], v[32:47]
	ds_read_b128 v[220:223], v12 offset:24576
	v_add_f32_e32 v248, v248, v122
	v_add_f32_e32 v249, v249, v123
	v_add_f32_e32 v248, v248, v124
	v_add_f32_e32 v249, v249, v125
	v_add_f32_e32 v248, v248, v126
	s_waitcnt lgkmcnt(7)
	v_mfma_f32_32x32x16_bf16 v[16:31], v[224:227], v[186:189], v[16:31]
	ds_read_b128 v[224:227], v12 offset:28672
	v_add_f32_e32 v249, v249, v127
	v_cvt_pk_bf16_f32 v190, v120, v121
	v_cvt_pk_bf16_f32 v191, v122, v123
	v_cvt_pk_bf16_f32 v192, v124, v125
	v_cvt_pk_bf16_f32 v193, v126, v127
	s_nop 0
	s_waitcnt lgkmcnt(7)
	v_mfma_f32_32x32x16_bf16 v[64:79], v[228:231], v[190:193], v[64:79]
	ds_read_b128 v[228:231], v13 offset:16384
	v_exp_f32_e32 v96, v96
	v_exp_f32_e32 v97, v97
	v_exp_f32_e32 v98, v98
	v_exp_f32_e32 v99, v99
	v_exp_f32_e32 v100, v100
	s_waitcnt lgkmcnt(7)
	v_mfma_f32_32x32x16_bf16 v[48:63], v[232:235], v[190:193], v[48:63]
	ds_read_b128 v[232:235], v13 offset:20480
	v_exp_f32_e32 v101, v101
	v_exp_f32_e32 v102, v102
	v_exp_f32_e32 v103, v103
	v_add_f32_e32 v248, v248, v96
	v_add_f32_e32 v249, v249, v97
	s_waitcnt lgkmcnt(7)
	v_mfma_f32_32x32x16_bf16 v[32:47], v[236:239], v[190:193], v[32:47]
	ds_read_b128 v[236:239], v13 offset:24576
	v_add_f32_e32 v248, v248, v98
	v_add_f32_e32 v249, v249, v99
	v_add_f32_e32 v248, v248, v100
	v_add_f32_e32 v249, v249, v101
	v_add_f32_e32 v248, v248, v102
	s_waitcnt lgkmcnt(7)
	v_mfma_f32_32x32x16_bf16 v[16:31], v[240:243], v[190:193], v[16:31]
	ds_read_b128 v[240:243], v13 offset:28672
	v_add_f32_e32 v249, v249, v103
	v_cvt_pk_bf16_f32 v244, v96, v97
	v_cvt_pk_bf16_f32 v245, v98, v99
	v_cvt_pk_bf16_f32 v246, v100, v101
	v_cvt_pk_bf16_f32 v247, v102, v103
	s_nop 0
	s_waitcnt lgkmcnt(7)
	v_mfma_f32_32x32x16_bf16 v[64:79], v[212:215], v[244:247], v[64:79]
	v_exp_f32_e32 v104, v104
	v_exp_f32_e32 v105, v105
	v_exp_f32_e32 v106, v106
	v_exp_f32_e32 v107, v107
	v_exp_f32_e32 v108, v108
	s_waitcnt lgkmcnt(6)
	v_mfma_f32_32x32x16_bf16 v[48:63], v[216:219], v[244:247], v[48:63]
	v_exp_f32_e32 v109, v109
	v_exp_f32_e32 v110, v110
	v_exp_f32_e32 v111, v111
	v_add_f32_e32 v248, v248, v104
	v_add_f32_e32 v249, v249, v105
	s_waitcnt lgkmcnt(5)
	v_mfma_f32_32x32x16_bf16 v[32:47], v[220:223], v[244:247], v[32:47]
	v_add_f32_e32 v248, v248, v106
	v_add_f32_e32 v249, v249, v107
	v_add_f32_e32 v248, v248, v108
	v_add_f32_e32 v249, v249, v109
	v_add_f32_e32 v248, v248, v110
	s_waitcnt lgkmcnt(4)
	v_mfma_f32_32x32x16_bf16 v[16:31], v[224:227], v[244:247], v[16:31]
	v_add_f32_e32 v249, v249, v111
	v_cvt_pk_bf16_f32 v2, v104, v105
	v_cvt_pk_bf16_f32 v3, v106, v107
	v_cvt_pk_bf16_f32 v4, v108, v109
	v_cvt_pk_bf16_f32 v5, v110, v111
	s_nop 0
	s_waitcnt lgkmcnt(3)
	v_mfma_f32_32x32x16_bf16 v[64:79], v[228:231], v[2:5], v[64:79]
	s_waitcnt lgkmcnt(2)
	v_mfma_f32_32x32x16_bf16 v[48:63], v[232:235], v[2:5], v[48:63]
	s_waitcnt lgkmcnt(1)
	v_mfma_f32_32x32x16_bf16 v[32:47], v[236:239], v[2:5], v[32:47]
	s_waitcnt lgkmcnt(0)
	v_mfma_f32_32x32x16_bf16 v[16:31], v[240:243], v[2:5], v[16:31]
	s_add_i32 s5, s65, 1
	s_add_i32 s64, s64, 0x8000
	s_add_i32 s63, s63, 64
	v_lshl_add_u64 v[154:155], v[154:155], 0, s[92:93]
	v_lshl_add_u64 v[152:153], v[152:153], 0, s[92:93]
	s_cmp_eq_u32 s65, s62
	s_cbranch_scc1 .Lmy_dexit
; template <int DK, int DV, int NM, bool CAUSAL> ...
;     ...
;   for (int kt = 0; kt < nkt; ++kt) {
;     if (kt + 2 < nkt) asm volatile("s_waitcnt vmcnt(%0)" ::"n"(2 * NLD) : "memory");
;     else if (kt + 1 < nkt) asm volatile("s_waitcnt vmcnt(%0)" ::"n"(NLD) : "memory");
;     else asm volatile("s_waitcnt vmcnt(0)" ::: "memory");
;     asm volatile("s_waitcnt lgkmcnt(0)" ::: "memory");
;     __builtin_amdgcn_s_barrier();
;     if (kt + 3 < nkt) issue(kt + 3);
;     const bool skip = CAUSAL && (kt * 64 > q0w + 31);
;     if (!skip) {
;       const char* base = smem + (kt & 3) * STAGE;
;       f32x16 s[2];
; #pragma unroll
;       for (int sb = 0; sb < 2; ++sb) {
; #pragma unroll
;         for (int i = 0; i < 16; ++i) s[sb][i] = 0.f;
;         const char* pk = base + (sb * 32 + l31) * 256;
; #pragma unroll
;         for (int kc = 0; kc < NKC16; ++kc) {
;           const bf16x8 a = *(const bf16x8*)(pk + (((mymap * (DK / 8) + kc * 2 + h) ^ (l31 & 15)) * 16));
;           s[sb] = MFMA(a, qf[kc], s[sb]);
;         }
;         __builtin_amdgcn_sched_barrier(0);
;       }
;       const bool need_mask = CAUSAL && (kt * 64 + 63 > q0w);
;       const char* pv = base + KBYTES + l31 * 128;
;       const int vsw = (l31 >> 1) & 7;
;       bf16x8 pf[4];
;       auto expo = [&](int sb) {
; #pragma unroll
;         for (int i = 0; i < 16; ++i) {
;           float pz = __builtin_amdgcn_exp2f(s[sb][i]);
;           if (need_mask) {
;             const int key = kt * 64 + sb * 32 + crow(i, h);
;             if (key > q0w + l31) pz = 0.f;
;           }
;           s[sb][i] = pz;
;         }
; #pragma unroll
;         for (int k2 = 0; k2 < 2; ++k2) {
;           u4 pu;
;           pu.x = pack2(s[sb][k2 * 8 + 0], s[sb][k2 * 8 + 1]);
;           pu.y = pack2(s[sb][k2 * 8 + 2], s[sb][k2 * 8 + 3]);
;           pu.z = pack2(s[sb][k2 * 8 + 4], s[sb][k2 * 8 + 5]);
;           pu.w = pack2(s[sb][k2 * 8 + 6], s[sb][k2 * 8 + 7]);
;           pf[sb * 2 + k2] = __builtin_bit_cast(bf16x8, pu);
;         }
;       };
;       auto pvmm = [&](int ks) {
;         lacc = MFMA(ones, pf[ks], lacc);
; #pragma unroll
;         for (int d = 0; d < NDVB; ++d) {
;           const u4 au = *(const u4*)(pv + d * 32 * 128 + (((ks * 2 + h) ^ vsw) * 16));
;           o[d] = MFMA(__builtin_bit_cast(bf16x8, au), pf[ks], o[d]);
;         }
;       };
;       expo(0);
;       pvmm(0); pvmm(1);
;       expo(1);
	s_mov_b32 s65, s5
	s_cmp_ge_u32 s65, s62
	s_cbranch_scc1 .LBB0_92
	s_waitcnt vmcnt(8)
	s_add_i32 s4, s65, 3
	s_cmp_ge_u32 s4, s61
	s_barrier
	s_cbranch_scc1 .LBB0_97
	s_add_i32 s4, s63, 63
	s_cmp_le_u32 s4, s100
	s_cbranch_scc0 .Lmy_d96
	s_cmp_eq_u32 s101, 1
	s_cbranch_scc1 .Lmy_dlate
	s_branch .Lmy_dearly
.Lmy_dlate:
	s_and_b32 s4, s64, 0x18000
	v_or_b32_e32 v0, s4, v170
	v_add_u32_e32 v6, v0, v174
	v_add_u32_e32 v7, v0, v175
	v_add_u32_e32 v8, v0, v173
	v_add_u32_e32 v9, v0, v172
	ds_read_b128 v[212:215], v6
	ds_read_b128 v[216:219], v7
	ds_read_b128 v[220:223], v8
	ds_read_b128 v[224:227], v9
	ds_read_b128 v[228:231], v6 offset:8192
	ds_read_b128 v[232:235], v7 offset:8192
	ds_read_b128 v[236:239], v8 offset:8192
	ds_read_b128 v[240:243], v9 offset:8192
	v_or_b32_e32 v0, s4, v168
	v_add_u32_e32 v10, v0, v167
	v_add_u32_e32 v11, v0, v166
	v_add_u32_e32 v12, v0, v164
	v_add_u32_e32 v13, v0, v163
	s_waitcnt lgkmcnt(7)
	v_mfma_f32_32x32x16_bf16 v[112:127], v[212:215], v[140:143], 0
	s_waitcnt lgkmcnt(6)
	v_mfma_f32_32x32x16_bf16 v[112:127], v[216:219], v[136:139], v[112:127]
	s_waitcnt lgkmcnt(5)
	v_mfma_f32_32x32x16_bf16 v[112:127], v[220:223], v[132:135], v[112:127]
	s_waitcnt lgkmcnt(4)
	v_mfma_f32_32x32x16_bf16 v[112:127], v[224:227], v[128:131], v[112:127]
	ds_read_b128 v[212:215], v10 offset:16384
	ds_read_b128 v[216:219], v10 offset:20480
	s_waitcnt lgkmcnt(5)
	v_mfma_f32_32x32x16_bf16 v[96:111], v[228:231], v[140:143], 0
	ds_read_b128 v[220:223], v10 offset:24576
	ds_read_b128 v[224:227], v10 offset:28672
	s_waitcnt lgkmcnt(6)
	v_mfma_f32_32x32x16_bf16 v[96:111], v[232:235], v[136:139], v[96:111]
	s_waitcnt lgkmcnt(5)
	v_mfma_f32_32x32x16_bf16 v[96:111], v[236:239], v[132:135], v[96:111]
	s_waitcnt lgkmcnt(4)
	v_mfma_f32_32x32x16_bf16 v[96:111], v[240:243], v[128:131], v[96:111]
	ds_read_b128 v[228:231], v11 offset:16384
	ds_read_b128 v[232:235], v11 offset:20480
	ds_read_b128 v[236:239], v11 offset:24576
	ds_read_b128 v[240:243], v11 offset:28672
	v_exp_f32_e32 v112, v112
	v_exp_f32_e32 v113, v113
	v_exp_f32_e32 v114, v114
	v_exp_f32_e32 v115, v115
	v_exp_f32_e32 v116, v116
	v_exp_f32_e32 v117, v117
	v_exp_f32_e32 v118, v118
	v_exp_f32_e32 v119, v119
	v_add_f32_e32 v248, v248, v112
	v_add_f32_e32 v249, v249, v113
	v_add_f32_e32 v248, v248, v114
	v_add_f32_e32 v249, v249, v115
	v_add_f32_e32 v248, v248, v116
	v_add_f32_e32 v249, v249, v117
	v_add_f32_e32 v248, v248, v118
	v_add_f32_e32 v249, v249, v119
	v_cvt_pk_bf16_f32 v186, v112, v113
	v_cvt_pk_bf16_f32 v187, v114, v115
	v_cvt_pk_bf16_f32 v188, v116, v117
	v_cvt_pk_bf16_f32 v189, v118, v119
	s_nop 0
	v_add_u32_e32 v0, s63, v171
	v_add_u32_e32 v6, 0xc0, v0
	v_add_u32_e32 v8, 0xc4, v0
	v_ashrrev_i32_e32 v7, 31, v6
	v_ashrrev_i32_e32 v9, 31, v8
	v_lshlrev_b64 v[6:7], 11, v[6:7]
	v_lshlrev_b64 v[8:9], 11, v[8:9]
	s_add_i32 s4, s64, 0x18000
	s_and_b32 s4, s4, 0x18000
	v_lshl_add_u64 v[6:7], v[148:149], 0, v[6:7]
	v_lshl_add_u64 v[8:9], v[146:147], 0, v[8:9]
	s_add_i32 s5, s4, s35
	s_add_i32 s4, s4, s60
	s_waitcnt lgkmcnt(7)
	v_mfma_f32_32x32x16_bf16 v[64:79], v[212:215], v[186:189], v[64:79]
	ds_read_b128 v[212:215], v12 offset:16384
	v_exp_f32_e32 v120, v120
	v_exp_f32_e32 v121, v121
	v_exp_f32_e32 v122, v122
	v_exp_f32_e32 v123, v123
	v_exp_f32_e32 v124, v124
	s_waitcnt lgkmcnt(7)
	v_mfma_f32_32x32x16_bf16 v[48:63], v[216:219], v[186:189], v[48:63]
	ds_read_b128 v[216:219], v12 offset:20480
	v_exp_f32_e32 v125, v125
	v_exp_f32_e32 v126, v126
	v_exp_f32_e32 v127, v127
	v_add_f32_e32 v248, v248, v120
	v_add_f32_e32 v249, v249, v121
	s_waitcnt lgkmcnt(7)
; #define MFMA(a, b, c) __builtin_amdgcn_mfma_f32_32x32x16_bf16((a), (b), (c), 0, 0, 0)
; template <int DK, int DV, int NM, bool CAUSAL> ...
;     ...
;   auto issue = [&](int kt) {
;     char* st = smem + (kt & 3) * STAGE;
; #pragma unroll
;     for (int i = 0; i < 2; ++i) {
;       const int r = (wu * 2 + i) * 4 + krow;
;       const int c = kslot ^ (r & 15);
;       if (KCHV == 16 || c < KCHV)
;         __builtin_amdgcn_global_load_lds((const unsigned*)(Kg + (size_t)(kt * 64 + r) * ldk + c * 8), (unsigned*)(st + (wu * 2 + i) * 1024), 16, 0, 0);
;     }
; #pragma unroll
;     for (int i = 0; i < NVI; ++i) {
;       const int d = (wu * NVI + i) * 8 + vrow;
;       const int c = vslot ^ ((d >> 1) & 7);
;       __builtin_amdgcn_global_load_lds((const unsigned*)(Vt + (size_t)d * ldv + kt * 64 + c * 8), (unsigned*)(st + KBYTES + (wu * NVI + i) * 1024), 16, 0, 0);
;     }
;   };
;     ...
;       auto pvmm = [&](int ks) {
;         lacc = MFMA(ones, pf[ks], lacc);
; #pragma unroll
;         for (int d = 0; d < NDVB; ++d) {
;           const u4 au = *(const u4*)(pv + d * 32 * 128 + (((ks * 2 + h) ^ vsw) * 16));
;           o[d] = MFMA(__builtin_bit_cast(bf16x8, au), pf[ks], o[d]);
;         }
;       };
;       expo(0);
;       pvmm(0); pvmm(1);
;       expo(1);
;       pvmm(2); pvmm(3);
;       __builtin_amdgcn_sched_barrier(0);
	v_mfma_f32_32x32x16_bf16 v[32:47], v[220:223], v[186:189], v[32:47]
	ds_read_b128 v[220:223], v12 offset:24576
	v_add_f32_e32 v248, v248, v122
	v_add_f32_e32 v249, v249, v123
	v_add_f32_e32 v248, v248, v124
	v_add_f32_e32 v249, v249, v125
	v_add_f32_e32 v248, v248, v126
	s_waitcnt lgkmcnt(7)
	v_mfma_f32_32x32x16_bf16 v[16:31], v[224:227], v[186:189], v[16:31]
	ds_read_b128 v[224:227], v12 offset:28672
	v_add_f32_e32 v249, v249, v127
	v_cvt_pk_bf16_f32 v190, v120, v121
	v_cvt_pk_bf16_f32 v191, v122, v123
	v_cvt_pk_bf16_f32 v192, v124, v125
	v_cvt_pk_bf16_f32 v193, v126, v127
	s_nop 0
	s_mov_b32 m0, s5
	s_waitcnt lgkmcnt(7)
	v_mfma_f32_32x32x16_bf16 v[64:79], v[228:231], v[190:193], v[64:79]
	global_load_lds_dwordx4 v[6:7], off
	ds_read_b128 v[228:231], v13 offset:16384
	v_exp_f32_e32 v96, v96
	v_exp_f32_e32 v97, v97
	v_exp_f32_e32 v98, v98
	v_exp_f32_e32 v99, v99
	v_exp_f32_e32 v100, v100
	s_mov_b32 m0, s4
	s_waitcnt lgkmcnt(7)
	v_mfma_f32_32x32x16_bf16 v[48:63], v[232:235], v[190:193], v[48:63]
	global_load_lds_dwordx4 v[8:9], off
	ds_read_b128 v[232:235], v13 offset:20480
	v_exp_f32_e32 v101, v101
	v_exp_f32_e32 v102, v102
	v_exp_f32_e32 v103, v103
	v_add_f32_e32 v248, v248, v96
	v_add_f32_e32 v249, v249, v97
	s_add_i32 m0, s5, 0x4000
	s_waitcnt lgkmcnt(7)
	v_mfma_f32_32x32x16_bf16 v[32:47], v[236:239], v[190:193], v[32:47]
	global_load_lds_dwordx4 v[152:153], off
	ds_read_b128 v[236:239], v13 offset:24576
	v_add_f32_e32 v248, v248, v98
	v_add_f32_e32 v249, v249, v99
	v_add_f32_e32 v248, v248, v100
	v_add_f32_e32 v249, v249, v101
	v_add_f32_e32 v248, v248, v102
	s_add_i32 m0, s4, 0x4000
	s_waitcnt lgkmcnt(7)
	v_mfma_f32_32x32x16_bf16 v[16:31], v[240:243], v[190:193], v[16:31]
	global_load_lds_dwordx4 v[154:155], off
	ds_read_b128 v[240:243], v13 offset:28672
	v_add_f32_e32 v249, v249, v103
	v_cvt_pk_bf16_f32 v244, v96, v97
	v_cvt_pk_bf16_f32 v245, v98, v99
	v_cvt_pk_bf16_f32 v246, v100, v101
	v_cvt_pk_bf16_f32 v247, v102, v103
	s_nop 0
	s_waitcnt lgkmcnt(7)
	v_mfma_f32_32x32x16_bf16 v[64:79], v[212:215], v[244:247], v[64:79]
	v_exp_f32_e32 v104, v104
	v_exp_f32_e32 v105, v105
	v_exp_f32_e32 v106, v106
	v_exp_f32_e32 v107, v107
	v_exp_f32_e32 v108, v108
	s_waitcnt lgkmcnt(6)
	v_mfma_f32_32x32x16_bf16 v[48:63], v[216:219], v[244:247], v[48:63]
	v_exp_f32_e32 v109, v109
	v_exp_f32_e32 v110, v110
	v_exp_f32_e32 v111, v111
	v_add_f32_e32 v248, v248, v104
	v_add_f32_e32 v249, v249, v105
	s_waitcnt lgkmcnt(5)
	v_mfma_f32_32x32x16_bf16 v[32:47], v[220:223], v[244:247], v[32:47]
	v_add_f32_e32 v248, v248, v106
	v_add_f32_e32 v249, v249, v107
	v_add_f32_e32 v248, v248, v108
	v_add_f32_e32 v249, v249, v109
	v_add_f32_e32 v248, v248, v110
	s_waitcnt lgkmcnt(4)
	v_mfma_f32_32x32x16_bf16 v[16:31], v[224:227], v[244:247], v[16:31]
	v_add_f32_e32 v249, v249, v111
	v_cvt_pk_bf16_f32 v2, v104, v105
	v_cvt_pk_bf16_f32 v3, v106, v107
	v_cvt_pk_bf16_f32 v4, v108, v109
	v_cvt_pk_bf16_f32 v5, v110, v111
	s_nop 0
	s_waitcnt lgkmcnt(3)
	v_mfma_f32_32x32x16_bf16 v[64:79], v[228:231], v[2:5], v[64:79]
	s_waitcnt lgkmcnt(2)
	v_mfma_f32_32x32x16_bf16 v[48:63], v[232:235], v[2:5], v[48:63]
	s_waitcnt lgkmcnt(1)
	v_mfma_f32_32x32x16_bf16 v[32:47], v[236:239], v[2:5], v[32:47]
	s_waitcnt lgkmcnt(0)
	v_mfma_f32_32x32x16_bf16 v[16:31], v[240:243], v[2:5], v[16:31]
	s_add_i32 s5, s65, 1
	s_add_i32 s64, s64, 0x8000
	s_add_i32 s63, s63, 64
	v_lshl_add_u64 v[154:155], v[154:155], 0, s[92:93]
	v_lshl_add_u64 v[152:153], v[152:153], 0, s[92:93]
	s_cmp_eq_u32 s65, s62
	s_cbranch_scc1 .Lmy_dexit
	s_mov_b32 s65, s5
	s_cmp_ge_u32 s65, s62
	s_cbranch_scc1 .LBB0_92
	s_waitcnt vmcnt(8)
	s_add_i32 s4, s65, 3
	s_cmp_ge_u32 s4, s61
	s_barrier
	s_cbranch_scc1 .LBB0_97
	s_add_i32 s4, s63, 63
	s_cmp_le_u32 s4, s100
	s_cbranch_scc0 .Lmy_d96
	s_cmp_eq_u32 s101, 1
	s_cbranch_scc1 .Lmy_dlate
	s_branch .Lmy_dearly

; #define MFMA(a, b, c) __builtin_amdgcn_mfma_f32_32x32x16_bf16((a), (b), (c), 0, 0, 0)
; DI unsigned pack2(float a, float b) { fl2_t f = {a, b}; bf2_t r = __builtin_convertvector(f, bf2_t); return __builtin_bit_cast(unsigned, r); }
; DI int crow(int i, int h) { return (i & 3) + 8 * (i >> 2) + 4 * h; }
; template <int DK, int DV, int NM, bool CAUSAL> ...
;     ...
;   for (int kt = 0; kt < nkt; ++kt) {
;     if (kt + 2 < nkt) asm volatile("s_waitcnt vmcnt(%0)" ::"n"(2 * NLD) : "memory");
;     else if (kt + 1 < nkt) asm volatile("s_waitcnt vmcnt(%0)" ::"n"(NLD) : "memory");
;     else asm volatile("s_waitcnt vmcnt(0)" ::: "memory");
;     asm volatile("s_waitcnt lgkmcnt(0)" ::: "memory");
;     __builtin_amdgcn_s_barrier();
;     if (kt + 3 < nkt) issue(kt + 3);
;     const bool skip = CAUSAL && (kt * 64 > q0w + 31);
;     if (!skip) {
;       const char* base = smem + (kt & 3) * STAGE;
;       f32x16 s[2];
; #pragma unroll
;       for (int sb = 0; sb < 2; ++sb) {
; #pragma unroll
;         for (int i = 0; i < 16; ++i) s[sb][i] = 0.f;
;         const char* pk = base + (sb * 32 + l31) * 256;
; #pragma unroll
;         for (int kc = 0; kc < NKC16; ++kc) {
;           const bf16x8 a = *(const bf16x8*)(pk + (((mymap * (DK / 8) + kc * 2 + h) ^ (l31 & 15)) * 16));
;           s[sb] = MFMA(a, qf[kc], s[sb]);
;         }
;         __builtin_amdgcn_sched_barrier(0);
;       }
;       const bool need_mask = CAUSAL && (kt * 64 + 63 > q0w);
;       const char* pv = base + KBYTES + l31 * 128;
;       const int vsw = (l31 >> 1) & 7;
;       bf16x8 pf[4];
;       auto expo = [&](int sb) {
; #pragma unroll
;         for (int i = 0; i < 16; ++i) {
;           float pz = __builtin_amdgcn_exp2f(s[sb][i]);
;           if (need_mask) {
;             const int key = kt * 64 + sb * 32 + crow(i, h);
;             if (key > q0w + l31) pz = 0.f;
;           }
;           s[sb][i] = pz;
;         }
; #pragma unroll
;         for (int k2 = 0; k2 < 2; ++k2) {
;           u4 pu;
;           pu.x = pack2(s[sb][k2 * 8 + 0], s[sb][k2 * 8 + 1]);
;           pu.y = pack2(s[sb][k2 * 8 + 2], s[sb][k2 * 8 + 3]);
;           pu.z = pack2(s[sb][k2 * 8 + 4], s[sb][k2 * 8 + 5]);
;           pu.w = pack2(s[sb][k2 * 8 + 6], s[sb][k2 * 8 + 7]);
;           pf[sb * 2 + k2] = __builtin_bit_cast(bf16x8, pu);
;         }
;       };
.Lmy_dexit:
	s_waitcnt vmcnt(0)
	s_waitcnt lgkmcnt(0)
	s_lshl_b32 s4, s5, 6
	v_cmp_le_u32_e32 vcc, s4, v176
	s_barrier
	s_and_saveexec_b64 s[16:17], vcc
	s_cbranch_execz .LBB0_102
	s_lshl_b32 s5, s5, 15
	s_and_b32 s5, s5, 0x18000
	v_or_b32_e32 v0, s5, v170
	v_add_u32_e32 v6, v0, v174
	ds_read_b128 v[2:5], v6
	v_add_u32_e32 v7, v0, v175
	v_add_u32_e32 v8, v0, v173
	v_add_u32_e32 v0, v0, v172
	s_waitcnt lgkmcnt(0)
	v_mfma_f32_32x32x16_bf16 v[112:127], v[2:5], v[140:143], 0
	ds_read_b128 v[2:5], v7
	s_waitcnt lgkmcnt(0)
	v_mfma_f32_32x32x16_bf16 v[112:127], v[2:5], v[136:139], v[112:127]
	ds_read_b128 v[2:5], v8
	s_waitcnt lgkmcnt(0)
	v_mfma_f32_32x32x16_bf16 v[112:127], v[2:5], v[132:135], v[112:127]
	ds_read_b128 v[2:5], v0
	s_waitcnt lgkmcnt(0)
	v_mfma_f32_32x32x16_bf16 v[112:127], v[2:5], v[128:131], v[112:127]
	ds_read_b128 v[2:5], v6 offset:8192
	s_waitcnt lgkmcnt(0)
	v_mfma_f32_32x32x16_bf16 v[96:111], v[2:5], v[140:143], 0
	ds_read_b128 v[2:5], v7 offset:8192
	s_waitcnt lgkmcnt(0)
	v_mfma_f32_32x32x16_bf16 v[96:111], v[2:5], v[136:139], v[96:111]
	ds_read_b128 v[2:5], v8 offset:8192
	s_waitcnt lgkmcnt(0)
	v_mfma_f32_32x32x16_bf16 v[96:111], v[2:5], v[132:135], v[96:111]
	ds_read_b128 v[2:5], v0 offset:8192
	s_waitcnt lgkmcnt(0)
	v_mfma_f32_32x32x16_bf16 v[96:111], v[2:5], v[128:131], v[96:111]
	v_exp_f32_e32 v2, v112
	s_or_b32 s35, s4, 63
	v_or_b32_e32 v14, s4, v160
	v_exp_f32_e32 v3, v113
	v_cmp_gt_u32_e32 vcc, s35, v169
	v_or_b32_e32 v0, s5, v168
	v_cmp_gt_u32_e64 s[4:5], v14, v165
	s_and_b64 s[4:5], vcc, s[4:5]
	v_or_b32_e32 v5, 2, v14
	v_cndmask_b32_e64 v2, v2, 0, s[4:5]
	v_cmp_lt_u32_e64 s[4:5], v14, v165
	v_or_b32_e32 v6, 3, v14
	v_or_b32_e32 v7, 8, v14
	v_cndmask_b32_e64 v4, 0, v3, s[4:5]
	v_cndmask_b32_e32 v3, v3, v4, vcc
	v_exp_f32_e32 v4, v114
	v_cmp_gt_u32_e64 s[4:5], v5, v165
	v_exp_f32_e32 v5, v115
	s_and_b64 s[4:5], vcc, s[4:5]
	v_cndmask_b32_e64 v4, v4, 0, s[4:5]
	v_cmp_gt_u32_e64 s[4:5], v6, v165
	v_exp_f32_e32 v6, v116
	s_and_b64 s[4:5], vcc, s[4:5]
	v_cndmask_b32_e64 v5, v5, 0, s[4:5]
	v_cmp_gt_u32_e64 s[4:5], v7, v165
	s_and_b64 s[4:5], vcc, s[4:5]
	v_or_b32_e32 v7, 9, v14
	v_cndmask_b32_e64 v8, v6, 0, s[4:5]
	v_exp_f32_e32 v6, v117
	v_cmp_gt_u32_e64 s[4:5], v7, v165
	s_and_b64 s[4:5], vcc, s[4:5]
	v_or_b32_e32 v7, 10, v14
	v_cndmask_b32_e64 v9, v6, 0, s[4:5]
	v_exp_f32_e32 v6, v118
	v_cmp_gt_u32_e64 s[4:5], v7, v165
	s_and_b64 s[4:5], vcc, s[4:5]
	v_or_b32_e32 v7, 11, v14
	v_cndmask_b32_e64 v10, v6, 0, s[4:5]
	v_exp_f32_e32 v6, v119
	v_cmp_gt_u32_e64 s[4:5], v7, v165
	s_and_b64 s[4:5], vcc, s[4:5]
	v_or_b32_e32 v7, 16, v14
	v_cndmask_b32_e64 v11, v6, 0, s[4:5]
	v_exp_f32_e32 v6, v120
	v_cmp_gt_u32_e64 s[4:5], v7, v165
	s_and_b64 s[4:5], vcc, s[4:5]
	v_or_b32_e32 v7, 17, v14
	v_cndmask_b32_e64 v12, v6, 0, s[4:5]
	v_exp_f32_e32 v6, v121
	v_cmp_gt_u32_e64 s[4:5], v7, v165
	s_and_b64 s[4:5], vcc, s[4:5]
	v_or_b32_e32 v7, 18, v14
	v_cndmask_b32_e64 v13, v6, 0, s[4:5]
	v_exp_f32_e32 v6, v122
	v_cmp_gt_u32_e64 s[4:5], v7, v165
	s_and_b64 s[4:5], vcc, s[4:5]
	v_or_b32_e32 v7, 19, v14
	v_cndmask_b32_e64 v15, v6, 0, s[4:5]
	v_exp_f32_e32 v6, v123
	v_cmp_gt_u32_e64 s[4:5], v7, v165
	s_and_b64 s[4:5], vcc, s[4:5]
	v_or_b32_e32 v7, 24, v14
	v_cndmask_b32_e64 v112, v6, 0, s[4:5]
	v_exp_f32_e32 v6, v124
	v_cmp_gt_u32_e64 s[4:5], v7, v165
	s_and_b64 s[4:5], vcc, s[4:5]
	v_or_b32_e32 v7, 25, v14
	v_cndmask_b32_e64 v113, v6, 0, s[4:5]
	v_exp_f32_e32 v6, v125
	v_cmp_gt_u32_e64 s[4:5], v7, v165
	s_and_b64 s[4:5], vcc, s[4:5]
	v_or_b32_e32 v7, 26, v14
	v_cndmask_b32_e64 v114, v6, 0, s[4:5]
	v_exp_f32_e32 v6, v126
	v_cmp_gt_u32_e64 s[4:5], v7, v165
	s_and_b64 s[4:5], vcc, s[4:5]
	v_or_b32_e32 v7, 27, v14
	v_cndmask_b32_e64 v115, v6, 0, s[4:5]
	v_exp_f32_e32 v6, v127
	v_cmp_gt_u32_e64 s[4:5], v7, v165
	s_and_b64 s[4:5], vcc, s[4:5]
	v_cvt_pk_bf16_f32 v8, v8, v9
	v_cndmask_b32_e64 v116, v6, 0, s[4:5]
	v_cvt_pk_bf16_f32 v9, v10, v11
	v_cvt_pk_bf16_f32 v11, v15, v112
	v_add_u32_e32 v15, v0, v167
	v_cvt_pk_bf16_f32 v10, v12, v13
	v_cvt_pk_bf16_f32 v12, v113, v114
	v_cvt_pk_bf16_f32 v13, v115, v116
	ds_read_b128 v[112:115], v15 offset:16384
	v_cvt_pk_bf16_f32 v6, v2, v3
	v_cvt_pk_bf16_f32 v7, v4, v5
	s_mov_b32 s85, s84
	s_mov_b32 s86, s84
	s_waitcnt lgkmcnt(0)
	v_mfma_f32_32x32x16_bf16 v[64:79], v[112:115], v[6:9], v[64:79]
	ds_read_b128 v[112:115], v15 offset:20480
	s_mov_b32 s87, s84
	v_mov_b64_e32 v[2:3], s[84:85]
	v_mov_b64_e32 v[4:5], s[86:87]
	s_waitcnt lgkmcnt(0)
	v_mfma_f32_32x32x16_bf16 v[48:63], v[112:115], v[6:9], v[48:63]
	ds_read_b128 v[112:115], v15 offset:24576
	s_waitcnt lgkmcnt(0)
; #define MFMA(a, b, c) __builtin_amdgcn_mfma_f32_32x32x16_bf16((a), (b), (c), 0, 0, 0)
; DI unsigned pack2(float a, float b) { fl2_t f = {a, b}; bf2_t r = __builtin_convertvector(f, bf2_t); return __builtin_bit_cast(unsigned, r); }
; DI int crow(int i, int h) { return (i & 3) + 8 * (i >> 2) + 4 * h; }
; template <int DK, int DV, int NM, bool CAUSAL> ...
;     ...
;       auto expo = [&](int sb) {
; #pragma unroll
;         for (int i = 0; i < 16; ++i) {
;           float pz = __builtin_amdgcn_exp2f(s[sb][i]);
;           if (need_mask) {
;             const int key = kt * 64 + sb * 32 + crow(i, h);
;             if (key > q0w + l31) pz = 0.f;
;           }
;           s[sb][i] = pz;
;         }
; #pragma unroll
;         for (int k2 = 0; k2 < 2; ++k2) {
;           u4 pu;
;           pu.x = pack2(s[sb][k2 * 8 + 0], s[sb][k2 * 8 + 1]);
;           pu.y = pack2(s[sb][k2 * 8 + 2], s[sb][k2 * 8 + 3]);
;           pu.z = pack2(s[sb][k2 * 8 + 4], s[sb][k2 * 8 + 5]);
;           pu.w = pack2(s[sb][k2 * 8 + 6], s[sb][k2 * 8 + 7]);
;           pf[sb * 2 + k2] = __builtin_bit_cast(bf16x8, pu);
;         }
;       };
;       auto pvmm = [&](int ks) {
;         lacc = MFMA(ones, pf[ks], lacc);
; #pragma unroll
;         for (int d = 0; d < NDVB; ++d) {
;           const u4 au = *(const u4*)(pv + d * 32 * 128 + (((ks * 2 + h) ^ vsw) * 16));
;           o[d] = MFMA(__builtin_bit_cast(bf16x8, au), pf[ks], o[d]);
;         }
;       };
;       expo(0);
;       pvmm(0); pvmm(1);
;       expo(1);
;       pvmm(2); pvmm(3);
;       __builtin_amdgcn_sched_barrier(0);
	v_mfma_f32_32x32x16_bf16 v[32:47], v[112:115], v[6:9], v[32:47]
	ds_read_b128 v[112:115], v15 offset:28672
	v_add_u32_e32 v15, v0, v166
	v_mfma_f32_32x32x16_bf16 v[80:95], v[2:5], v[6:9], v[80:95]
	s_waitcnt lgkmcnt(0)
	v_mfma_f32_32x32x16_bf16 v[16:31], v[112:115], v[6:9], v[16:31]
	ds_read_b128 v[6:9], v15 offset:16384
	s_waitcnt lgkmcnt(0)
	v_mfma_f32_32x32x16_bf16 v[64:79], v[6:9], v[10:13], v[64:79]
	ds_read_b128 v[6:9], v15 offset:20480
	s_waitcnt lgkmcnt(0)
	v_mfma_f32_32x32x16_bf16 v[48:63], v[6:9], v[10:13], v[48:63]
	ds_read_b128 v[6:9], v15 offset:24576
	s_waitcnt lgkmcnt(0)
	v_mfma_f32_32x32x16_bf16 v[32:47], v[6:9], v[10:13], v[32:47]
	ds_read_b128 v[6:9], v15 offset:28672
	v_or_b32_e32 v15, 43, v14
	s_waitcnt lgkmcnt(0)
	v_mfma_f32_32x32x16_bf16 v[16:31], v[6:9], v[10:13], v[16:31]
	v_exp_f32_e32 v6, v96
	v_or_b32_e32 v7, 32, v14
	v_cmp_gt_u32_e64 s[4:5], v7, v165
	v_exp_f32_e32 v7, v97
	s_and_b64 s[4:5], vcc, s[4:5]
	v_or_b32_e32 v8, 33, v14
	v_cndmask_b32_e64 v6, v6, 0, s[4:5]
	v_cmp_gt_u32_e64 s[4:5], v8, v165
	v_exp_f32_e32 v8, v98
	s_and_b64 s[4:5], vcc, s[4:5]
	v_or_b32_e32 v9, 34, v14
	v_cndmask_b32_e64 v7, v7, 0, s[4:5]
	v_cmp_gt_u32_e64 s[4:5], v9, v165
	v_exp_f32_e32 v9, v99
	v_mfma_f32_32x32x16_bf16 v[80:95], v[2:5], v[10:13], v[80:95]
	s_and_b64 s[4:5], vcc, s[4:5]
	v_or_b32_e32 v10, 35, v14
	v_cndmask_b32_e64 v8, v8, 0, s[4:5]
	v_cmp_gt_u32_e64 s[4:5], v10, v165
	v_exp_f32_e32 v10, v100
	s_and_b64 s[4:5], vcc, s[4:5]
	v_or_b32_e32 v11, 40, v14
	v_cndmask_b32_e64 v9, v9, 0, s[4:5]
	v_cmp_gt_u32_e64 s[4:5], v11, v165
	v_exp_f32_e32 v11, v101
	s_and_b64 s[4:5], vcc, s[4:5]
	v_or_b32_e32 v12, 41, v14
	v_cndmask_b32_e64 v10, v10, 0, s[4:5]
	v_cmp_gt_u32_e64 s[4:5], v12, v165
	v_exp_f32_e32 v12, v102
	s_and_b64 s[4:5], vcc, s[4:5]
	v_or_b32_e32 v13, 42, v14
	v_cndmask_b32_e64 v11, v11, 0, s[4:5]
	v_cmp_gt_u32_e64 s[4:5], v13, v165
	v_exp_f32_e32 v13, v103
	s_and_b64 s[4:5], vcc, s[4:5]
	v_cndmask_b32_e64 v12, v12, 0, s[4:5]
	v_cmp_gt_u32_e64 s[4:5], v15, v165
	v_exp_f32_e32 v15, v104
	s_and_b64 s[4:5], vcc, s[4:5]
	v_or_b32_e32 v96, 48, v14
	v_cndmask_b32_e64 v13, v13, 0, s[4:5]
	v_cmp_gt_u32_e64 s[4:5], v96, v165
	v_exp_f32_e32 v96, v105
	s_and_b64 s[4:5], vcc, s[4:5]
	v_or_b32_e32 v97, 49, v14
	v_cndmask_b32_e64 v15, v15, 0, s[4:5]
	v_cmp_gt_u32_e64 s[4:5], v97, v165
	v_exp_f32_e32 v97, v106
	s_and_b64 s[4:5], vcc, s[4:5]
	v_or_b32_e32 v98, 50, v14
	v_cndmask_b32_e64 v96, v96, 0, s[4:5]
	v_cmp_gt_u32_e64 s[4:5], v98, v165
	v_exp_f32_e32 v98, v107
	s_and_b64 s[4:5], vcc, s[4:5]
	v_or_b32_e32 v99, 51, v14
	v_cndmask_b32_e64 v97, v97, 0, s[4:5]
	v_cmp_gt_u32_e64 s[4:5], v99, v165
	v_exp_f32_e32 v99, v108
	s_and_b64 s[4:5], vcc, s[4:5]
	v_or_b32_e32 v100, 56, v14
	v_cndmask_b32_e64 v98, v98, 0, s[4:5]
	v_cmp_gt_u32_e64 s[4:5], v100, v165
	v_exp_f32_e32 v100, v109
	s_and_b64 s[4:5], vcc, s[4:5]
	v_or_b32_e32 v101, 57, v14
	v_cndmask_b32_e64 v99, v99, 0, s[4:5]
	v_cmp_gt_u32_e64 s[4:5], v101, v165
	v_exp_f32_e32 v101, v110
	s_and_b64 s[4:5], vcc, s[4:5]
	v_or_b32_e32 v102, 58, v14
	v_cndmask_b32_e64 v100, v100, 0, s[4:5]
	v_cmp_gt_u32_e64 s[4:5], v102, v165
	v_exp_f32_e32 v102, v111
	s_and_b64 s[4:5], vcc, s[4:5]
	v_or_b32_e32 v14, 59, v14
	v_cndmask_b32_e64 v101, v101, 0, s[4:5]
	v_cmp_gt_u32_e64 s[4:5], v14, v165
	s_and_b64 s[4:5], vcc, s[4:5]
	v_cvt_pk_bf16_f32 v6, v6, v7
	v_cndmask_b32_e64 v14, v102, 0, s[4:5]
	v_cvt_pk_bf16_f32 v7, v8, v9
	v_cvt_pk_bf16_f32 v8, v10, v11
	v_cvt_pk_bf16_f32 v9, v12, v13
	v_cvt_pk_bf16_f32 v13, v101, v14
	v_add_u32_e32 v14, v0, v164
	v_cvt_pk_bf16_f32 v10, v15, v96
	v_cvt_pk_bf16_f32 v11, v97, v98
	v_cvt_pk_bf16_f32 v12, v99, v100
	v_mfma_f32_32x32x16_bf16 v[80:95], v[2:5], v[6:9], v[80:95]
	ds_read_b128 v[96:99], v14 offset:16384
	v_add_u32_e32 v0, v0, v163
	v_mfma_f32_32x32x16_bf16 v[80:95], v[2:5], v[10:13], v[80:95]
	ds_read_b128 v[2:5], v0 offset:16384
	s_waitcnt lgkmcnt(0)
	v_mfma_f32_32x32x16_bf16 v[64:79], v[96:99], v[6:9], v[64:79]
	ds_read_b128 v[96:99], v14 offset:20480
	v_mfma_f32_32x32x16_bf16 v[64:79], v[2:5], v[10:13], v[64:79]
	ds_read_b128 v[2:5], v0 offset:20480
	s_waitcnt lgkmcnt(0)
	v_mfma_f32_32x32x16_bf16 v[48:63], v[96:99], v[6:9], v[48:63]
	ds_read_b128 v[96:99], v14 offset:24576
	v_mfma_f32_32x32x16_bf16 v[48:63], v[2:5], v[10:13], v[48:63]
	ds_read_b128 v[2:5], v0 offset:24576
	s_waitcnt lgkmcnt(0)
	v_mfma_f32_32x32x16_bf16 v[32:47], v[96:99], v[6:9], v[32:47]
	ds_read_b128 v[96:99], v14 offset:28672
	v_mfma_f32_32x32x16_bf16 v[32:47], v[2:5], v[10:13], v[32:47]
	ds_read_b128 v[2:5], v0 offset:28672
	s_waitcnt lgkmcnt(0)
	v_mfma_f32_32x32x16_bf16 v[16:31], v[96:99], v[6:9], v[16:31]
	v_mfma_f32_32x32x16_bf16 v[16:31], v[2:5], v[10:13], v[16:31]

; #define STAGE8(Q, BASE, br, kt) do { const bf16_t* sb_ = (BASE) + ((long)(br) * K + (long)(kt) * BK8); \
;     _Pragma("unroll") for (int i_ = 0; i_ < 2; ++i_) \
;       __builtin_amdgcn_global_load_lds((const unsigned*)(sb_ + goff[i_]), (unsigned*)(smem + (Q) * HTB + i_ * 8192 + wu8 * 1024), 16, 0, 0); } while (0)
; #define WAIT_V8(n) asm volatile("s_waitcnt vmcnt(" #n ")" ::: "memory")
; #define BAR8 __builtin_amdgcn_s_barrier()
; DI void gemm8p(const bf16_t* __restrict__ A, const bf16_t* __restrict__ Bt, int K, f32x4v (&acc)[2][2][4][2], char* smem) {
;     ...
; #pragma unroll
;   for (int a = 0; a < 2; ++a)
; #pragma unroll
;     for (int b = 0; b < 2; ++b)
; #pragma unroll
;       for (int m = 0; m < 4; ++m)
; #pragma unroll
;         for (int n = 0; n < 2; ++n) acc[a][b][m][n] = f32x4v{0.f, 0.f, 0.f, 0.f};
;   bf16x8 At[4][2], B0[2][2], B1[2][2];
;   const int nt = K / BK8;
;   asm volatile("s_waitcnt vmcnt(0)" ::: "memory");
;   __syncthreads();
;   STAGE8(SB8(0, 0), Bt, 0, 0); STAGE8(SA8(0, 0), A, 0, 0);
;   STAGE8(SB8(0, 1), Bt, HALF8, 0); STAGE8(SA8(0, 1), A, HALF8, 0);
;   if (wr == 1) BAR8;
;   WAIT_V8(4); BAR8;
;   STAGE8(SB8(1, 0), Bt, 0, 1); STAGE8(SA8(1, 0), A, 0, 1); STAGE8(SB8(1, 1), Bt, HALF8, 1);
;   WAIT_V8(6); BAR8;
.LBB0_463:
	s_or_b64 exec, exec, s[8:9]
	s_xor_b64 s[6:7], s[6:7], -1
	v_writelane_b32 v250, s6, 12
	v_lshl_add_u64 v[2:3], v[2:3], 0, s[92:93]
	s_waitcnt vmcnt(4)
	s_barrier
	v_writelane_b32 v250, s7, 13
	s_add_i32 s6, s10, 0x18000
	s_mov_b32 m0, s6
	s_add_i32 s7, s10, 0x1a000
	global_load_lds_dwordx4 v[2:3], off
	v_lshl_add_u64 v[2:3], v[4:5], 0, s[92:93]
	s_mov_b32 m0, s7
	s_add_i32 s8, s10, 0x8000
	global_load_lds_dwordx4 v[2:3], off
	v_lshl_add_u64 v[2:3], v[8:9], 0, s[92:93]
	s_mov_b32 m0, s8
	s_add_i32 s9, s10, 0xa000
	global_load_lds_dwordx4 v[2:3], off
	v_lshl_add_u64 v[2:3], v[6:7], 0, s[92:93]
	s_mov_b32 m0, s9
	s_add_i32 s30, s10, 0x1c000
	global_load_lds_dwordx4 v[2:3], off
	v_lshl_add_u64 v[2:3], v[10:11], 0, s[92:93]
	s_mov_b32 m0, s30
	s_add_i32 s31, s10, 0x1e000
	global_load_lds_dwordx4 v[2:3], off
	v_lshl_add_u64 v[2:3], v[12:13], 0, s[92:93]
	s_mov_b32 m0, s31
	s_xor_b64 s[4:5], s[4:5], -1
	global_load_lds_dwordx4 v[2:3], off
	v_and_b32_e32 v23, 15, v148
	v_lshlrev_b32_e32 v24, 2, v148
	v_lshlrev_b32_e32 v21, 12, v21
	s_waitcnt vmcnt(6)
	v_add3_u32 v2, v20, v18, v19
	v_mov_b32_e32 v3, v1
	v_add3_u32 v4, v16, v14, v15
	v_mov_b32_e32 v5, v1
	v_writelane_b32 v250, s4, 14
	v_and_b32_e32 v22, 48, v148
	v_lshlrev_b32_e32 v23, 6, v23
	v_and_b32_e32 v24, 32, v24
	v_and_b32_e32 v21, 0x3000, v21
	v_lshlrev_b64 v[2:3], 1, v[2:3]
	v_lshlrev_b64 v[4:5], 1, v[4:5]
	s_lshl_b64 s[52:53], s[80:81], 8
	v_writelane_b32 v250, s5, 15
	v_lshlrev_b32_e32 v17, 13, v17
	v_or_b32_e32 v21, 0x10000, v21
	v_bitop3_b32 v22, v23, v24, v22 bitop3:0x36
	s_lshr_b32 s5, s80, 6
	v_lshl_add_u64 v[132:133], s[0:1], 0, v[2:3]
	v_lshl_add_u64 v[6:7], s[52:53], 0, v[2:3]
	v_lshl_add_u64 v[8:9], s[52:53], 0, v[4:5]
	v_lshl_add_u64 v[140:141], s[2:3], 0, v[2:3]
	v_mov_b32_e32 v2, 0
	s_lshl_b32 s4, s80, 7
	s_barrier
	s_add_i32 s35, s5, -2
	v_lshl_add_u64 v[134:135], s[0:1], 0, v[4:5]
	v_lshl_add_u64 v[136:137], s[2:3], 0, v[6:7]
	v_lshl_add_u64 v[138:139], s[2:3], 0, v[8:9]
	v_lshl_add_u64 v[142:143], s[2:3], 0, v[4:5]
	v_lshl_add_u64 v[144:145], s[0:1], 0, v[8:9]
	v_lshl_add_u64 v[146:147], s[0:1], 0, v[6:7]
	s_mov_b32 s52, 0
	s_mov_b64 s[2:3], 0
	s_add_i32 s34, s10, 0xe000
	v_add_u32_e32 v150, v21, v22
	v_add_u32_e32 v149, v17, v22
	v_mov_b32_e32 v3, v2
	v_mov_b32_e32 v4, v2
	v_mov_b32_e32 v5, v2
	v_mov_b32_e32 v6, v2
	v_mov_b32_e32 v7, v2
	v_mov_b32_e32 v8, v2
	v_mov_b32_e32 v9, v2
	v_mov_b32_e32 v10, v2
	v_mov_b32_e32 v11, v2
	v_mov_b32_e32 v12, v2
	v_mov_b32_e32 v13, v2
	v_mov_b32_e32 v14, v2
	v_mov_b32_e32 v15, v2
	v_mov_b32_e32 v16, v2
	v_mov_b32_e32 v17, v2
	v_mov_b32_e32 v18, v2
	v_mov_b32_e32 v19, v2
	v_mov_b32_e32 v20, v2
	v_mov_b32_e32 v21, v2
	v_mov_b32_e32 v22, v2
	v_mov_b32_e32 v23, v2
	v_mov_b32_e32 v24, v2
	v_mov_b32_e32 v25, v2
	v_mov_b32_e32 v26, v2
	v_mov_b32_e32 v27, v2
	v_mov_b32_e32 v28, v2
	v_mov_b32_e32 v29, v2
	v_mov_b32_e32 v30, v2
	v_mov_b32_e32 v31, v2
	v_mov_b32_e32 v32, v2
	v_mov_b32_e32 v33, v2
	v_mov_b32_e32 v34, v2
	v_mov_b32_e32 v35, v2
	v_mov_b32_e32 v36, v2
	v_mov_b32_e32 v37, v2
	v_mov_b32_e32 v38, v2
	v_mov_b32_e32 v39, v2
	v_mov_b32_e32 v40, v2
	v_mov_b32_e32 v41, v2
	v_mov_b32_e32 v42, v2
	v_mov_b32_e32 v43, v2
	v_mov_b32_e32 v44, v2
	v_mov_b32_e32 v45, v2
	v_mov_b32_e32 v46, v2
	v_mov_b32_e32 v47, v2
	v_mov_b32_e32 v48, v2
	v_mov_b32_e32 v49, v2
	v_mov_b32_e32 v50, v2
	v_mov_b32_e32 v51, v2
	v_mov_b32_e32 v52, v2
	v_mov_b32_e32 v53, v2
	v_mov_b32_e32 v54, v2
	v_mov_b32_e32 v55, v2
	v_mov_b32_e32 v56, v2
	v_mov_b32_e32 v57, v2
	v_mov_b32_e32 v58, v2
	v_mov_b32_e32 v59, v2
	v_mov_b32_e32 v60, v2
	v_mov_b32_e32 v61, v2
	v_mov_b32_e32 v62, v2
	v_mov_b32_e32 v63, v2
	v_mov_b32_e32 v64, v2
	v_mov_b32_e32 v65, v2
	v_mov_b32_e32 v66, v2
	v_mov_b32_e32 v67, v2
	v_mov_b32_e32 v68, v2
	v_mov_b32_e32 v69, v2
	v_mov_b32_e32 v70, v2
	v_mov_b32_e32 v71, v2
	v_mov_b32_e32 v72, v2
	v_mov_b32_e32 v73, v2
	v_mov_b32_e32 v74, v2
	v_mov_b32_e32 v75, v2
	v_mov_b32_e32 v76, v2
	v_mov_b32_e32 v77, v2
	v_mov_b32_e32 v78, v2
	v_mov_b32_e32 v79, v2
	v_mov_b32_e32 v80, v2
	v_mov_b32_e32 v81, v2
	v_mov_b32_e32 v82, v2
	v_mov_b32_e32 v83, v2
	v_mov_b32_e32 v84, v2
	v_mov_b32_e32 v85, v2
	v_mov_b32_e32 v86, v2
	v_mov_b32_e32 v87, v2
	v_mov_b32_e32 v88, v2
	v_mov_b32_e32 v89, v2
	v_mov_b32_e32 v90, v2
	v_mov_b32_e32 v91, v2
	v_mov_b32_e32 v92, v2
	v_mov_b32_e32 v93, v2
	v_mov_b32_e32 v94, v2
	v_mov_b32_e32 v95, v2
	v_mov_b32_e32 v96, v2
	v_mov_b32_e32 v97, v2
	v_mov_b32_e32 v98, v2
	v_mov_b32_e32 v99, v2
	v_mov_b32_e32 v100, v2
	v_mov_b32_e32 v101, v2
	v_mov_b32_e32 v102, v2
	v_mov_b32_e32 v103, v2
	v_mov_b32_e32 v104, v2
	v_mov_b32_e32 v105, v2
	v_mov_b32_e32 v106, v2
	v_mov_b32_e32 v107, v2
	v_mov_b32_e32 v108, v2
	v_mov_b32_e32 v109, v2
	v_mov_b32_e32 v110, v2
	v_mov_b32_e32 v111, v2
	v_mov_b32_e32 v112, v2
	v_mov_b32_e32 v113, v2
	v_mov_b32_e32 v114, v2
	v_mov_b32_e32 v115, v2
	v_mov_b32_e32 v116, v2
	v_mov_b32_e32 v117, v2
	v_mov_b32_e32 v118, v2
	v_mov_b32_e32 v119, v2
	v_mov_b32_e32 v120, v2
	v_mov_b32_e32 v121, v2
	v_mov_b32_e32 v122, v2
	v_mov_b32_e32 v123, v2
	v_mov_b32_e32 v124, v2
	v_mov_b32_e32 v125, v2
	v_mov_b32_e32 v126, v2
	v_mov_b32_e32 v127, v2
	v_mov_b32_e32 v128, v2
	v_mov_b32_e32 v129, v2
	s_nop 0
	s_nop 0
	s_nop 0
	s_nop 0
	s_nop 0
	s_nop 0
	s_nop 0
	s_nop 0
	s_nop 0
	s_nop 0
	s_nop 0
	s_nop 0
	s_nop 0
	s_nop 0
	s_nop 0
